# retention: operand streams requested a full chunk ahead with counted vmcnt waits (44/42/14), unconditional requests
# baseline (speedup 1.0000x reference)
.LBB0_588:
	s_waitcnt vmcnt(0)
	s_add_i32 s84, s84, s33
	s_add_i32 s92, s92, s33
	s_cmpk_lt_i32 s84, 0x100
	s_cbranch_scc0 .LBB0_616
	v_lshrrev_b32_e32 v156, 3, v0
	v_bfe_u32 v4, v0, 5, 1
	v_xor_b32_e32 v5, 63, v156
	v_cvt_f32_ubyte0_e32 v194, v5
	v_and_b32_e32 v6, 12, v0
	v_lshl_or_b32 v6, v4, 1, v6
	v_mov_b32_e32 v5, 0x11000
	v_mad_u32_u24 v196, v6, s93, 0
	v_mov_b32_e32 v7, 0x90
	v_mad_u32_u24 v197, v6, v7, v5
	v_bfe_u32 v6, v0, 2, 2
	v_lshl_or_b32 v6, v4, 3, v6
	v_mad_u32_u24 v200, v6, v7, v5
	v_lshrrev_b32_e32 v154, 4, v0
	v_lshlrev_b32_e32 v155, 2, v4
	v_lshrrev_b32_e32 v6, 2, v0
	v_and_b32_e32 v157, 8, v6
	v_and_b32_e32 v6, 31, v0
	v_or_b32_e32 v199, 32, v6
	v_lshlrev_b32_e32 v8, 1, v6
	v_lshl_or_b32 v166, v4, 14, v8
	v_lshlrev_b32_e32 v6, 2, v0
	v_and_b32_e32 v6, 12, v6
	v_and_or_b32 v201, v0, 16, v6
	v_add_u32_e32 v195, 0, v158
	v_lshlrev_b32_e32 v160, 10, v4
	v_or_b32_e32 v198, 8, v155
	v_or_b32_e32 v206, 9, v155
	v_or_b32_e32 v207, 10, v155
	v_or_b32_e32 v208, 11, v155
	v_or_b32_e32 v209, 16, v155
	v_or_b32_e32 v210, 17, v155
	v_or_b32_e32 v211, 18, v155
	v_or_b32_e32 v212, 19, v155
	v_or_b32_e32 v213, 24, v155
	v_or_b32_e32 v214, 25, v155
	v_or_b32_e32 v215, 26, v155
	v_or_b32_e32 v216, 27, v155
	v_mov_b32_e32 v161, v2
	v_mov_b32_e32 v163, v2
	v_mov_b32_e32 v165, v2
	v_mov_b32_e32 v167, v2
	v_add_u32_e32 v217, 0x15800, v158
	v_and_b32_e32 v6, 15, v0
	v_lshlrev_b32_e32 v6, 4, v6
	v_lshl_or_b32 v162, v154, 11, v6
	v_and_b32_e32 v6, 7, v0
	v_lshlrev_b32_e32 v6, 4, v6
	v_lshl_or_b32 v164, v156, 12, v6

.LBB0_590:
	v_lshl_add_u64 v[12:13], s[82:83], 0, v[8:9]
	s_mov_b32 s4, 0x100000
	v_add_co_u32_e32 v70, vcc, s4, v12
	v_lshl_add_u64 v[10:11], s[82:83], 0, v[6:7]
	s_mov_b32 s5, 0x101000
	v_addc_co_u32_e32 v71, vcc, 0, v13, vcc
	global_load_dword v3, v[10:11], off
	v_add_co_u32_e32 v102, vcc, s5, v12
	v_lshl_add_u64 v[74:75], s[82:83], 0, v[4:5]
	s_nop 0
	v_addc_co_u32_e32 v103, vcc, 0, v13, vcc
	global_load_dwordx4 v[10:13], v[102:103], off offset:-4096
	global_load_dwordx4 v[14:17], v[70:71], off offset:512
	global_load_dwordx4 v[50:53], v[70:71], off offset:32
	global_load_dwordx4 v[54:57], v[70:71], off offset:544
	global_load_dwordx4 v[58:61], v[70:71], off offset:64
	global_load_dwordx4 v[62:65], v[70:71], off offset:576
	global_load_dwordx4 v[66:69], v[70:71], off offset:96
	s_nop 0
	global_load_dwordx4 v[70:73], v[70:71], off offset:608
	s_nop 0
	global_load_dword v107, v[74:75], off
	s_nop 0
	global_load_dwordx4 v[74:77], v[102:103], off
	global_load_dwordx4 v[78:81], v[102:103], off offset:512
	global_load_dwordx4 v[82:85], v[102:103], off offset:32
	global_load_dwordx4 v[86:89], v[102:103], off offset:544
	global_load_dwordx4 v[90:93], v[102:103], off offset:64
	global_load_dwordx4 v[94:97], v[102:103], off offset:576
	global_load_dwordx4 v[98:101], v[102:103], off offset:96
	s_nop 0
	global_load_dwordx4 v[102:105], v[102:103], off offset:608
	s_add_i32 s11, s7, 1
	v_cvt_f32_u32_e32 v106, s7
	v_cvt_f32_u32_e32 v108, s11
	s_mov_b64 s[4:5], 0x2000
	v_lshl_add_u64 v[8:9], v[8:9], 0, s[4:5]
	v_mul_f32_e32 v109, v224, v106
	v_mul_f32_e32 v110, v224, v108
	v_cmp_gt_f32_e32 vcc, s0, v109
	v_cmp_gt_f32_e64 s[4:5], s0, v110
	v_lshl_add_u64 v[4:5], v[4:5], 0, s[94:95]
	v_cndmask_b32_e32 v109, 0, v220, vcc
	v_cndmask_b32_e64 v110, 0, v220, s[4:5]
	v_fmac_f32_e32 v109, v224, v106
	v_fmac_f32_e32 v110, v224, v108
	v_exp_f32_e32 v106, v109
	v_exp_f32_e32 v108, v110
	s_and_b64 s[4:5], s[4:5], exec
	s_cselect_b32 s11, 0xffffffc0, 0
	s_and_b64 s[4:5], vcc, exec
	s_cselect_b32 s4, 0xffffffc0, 0
	v_ldexp_f32 v109, v106, s4
	v_ldexp_f32 v106, v108, s11
	s_add_i32 s7, s7, -2
	v_lshl_add_u64 v[6:7], v[6:7], 0, s[94:95]
	s_cmp_eq_u32 s7, -2
	s_waitcnt vmcnt(0)
	v_mul_f32_e32 v106, v3, v106
	v_pk_fma_f32 v[10:11], v[106:107], v[10:11], v[18:19] op_sel_hi:[0,1,1]
	v_pk_fma_f32 v[14:15], v[106:107], v[14:15], v[34:35] op_sel_hi:[0,1,1]
	v_pk_fma_f32 v[12:13], v[106:107], v[12:13], v[20:21] op_sel_hi:[0,1,1]
	v_pk_fma_f32 v[16:17], v[106:107], v[16:17], v[36:37] op_sel_hi:[0,1,1]
	v_pk_fma_f32 v[22:23], v[106:107], v[50:51], v[22:23] op_sel_hi:[0,1,1]
	v_pk_fma_f32 v[38:39], v[106:107], v[54:55], v[38:39] op_sel_hi:[0,1,1]
	v_pk_fma_f32 v[24:25], v[106:107], v[52:53], v[24:25] op_sel_hi:[0,1,1]
	v_pk_fma_f32 v[40:41], v[106:107], v[56:57], v[40:41] op_sel_hi:[0,1,1]
	v_pk_fma_f32 v[26:27], v[106:107], v[58:59], v[26:27] op_sel_hi:[0,1,1]
	v_pk_fma_f32 v[42:43], v[106:107], v[62:63], v[42:43] op_sel_hi:[0,1,1]
	v_pk_fma_f32 v[28:29], v[106:107], v[60:61], v[28:29] op_sel_hi:[0,1,1]
	v_pk_fma_f32 v[44:45], v[106:107], v[64:65], v[44:45] op_sel_hi:[0,1,1]
	v_pk_fma_f32 v[30:31], v[106:107], v[66:67], v[30:31] op_sel_hi:[0,1,1]
	v_pk_fma_f32 v[46:47], v[106:107], v[70:71], v[46:47] op_sel_hi:[0,1,1]
	v_pk_fma_f32 v[32:33], v[106:107], v[68:69], v[32:33] op_sel_hi:[0,1,1]
	v_pk_fma_f32 v[48:49], v[106:107], v[72:73], v[48:49] op_sel_hi:[0,1,1]
	v_mul_f32_e32 v50, v107, v109
	v_pk_fma_f32 v[18:19], v[50:51], v[74:75], v[10:11] op_sel_hi:[0,1,1]
	v_pk_fma_f32 v[34:35], v[50:51], v[78:79], v[14:15] op_sel_hi:[0,1,1]
	v_pk_fma_f32 v[20:21], v[50:51], v[76:77], v[12:13] op_sel_hi:[0,1,1]
	v_pk_fma_f32 v[36:37], v[50:51], v[80:81], v[16:17] op_sel_hi:[0,1,1]
	v_pk_fma_f32 v[22:23], v[50:51], v[82:83], v[22:23] op_sel_hi:[0,1,1]
	v_pk_fma_f32 v[38:39], v[50:51], v[86:87], v[38:39] op_sel_hi:[0,1,1]
	v_pk_fma_f32 v[24:25], v[50:51], v[84:85], v[24:25] op_sel_hi:[0,1,1]
	v_pk_fma_f32 v[40:41], v[50:51], v[88:89], v[40:41] op_sel_hi:[0,1,1]
	v_pk_fma_f32 v[26:27], v[50:51], v[90:91], v[26:27] op_sel_hi:[0,1,1]
	v_pk_fma_f32 v[42:43], v[50:51], v[94:95], v[42:43] op_sel_hi:[0,1,1]
	v_pk_fma_f32 v[28:29], v[50:51], v[92:93], v[28:29] op_sel_hi:[0,1,1]
	v_pk_fma_f32 v[44:45], v[50:51], v[96:97], v[44:45] op_sel_hi:[0,1,1]
	v_pk_fma_f32 v[30:31], v[50:51], v[98:99], v[30:31] op_sel_hi:[0,1,1]
	v_pk_fma_f32 v[46:47], v[50:51], v[102:103], v[46:47] op_sel_hi:[0,1,1]
	v_pk_fma_f32 v[32:33], v[50:51], v[100:101], v[32:33] op_sel_hi:[0,1,1]
	v_pk_fma_f32 v[48:49], v[50:51], v[104:105], v[48:49] op_sel_hi:[0,1,1]
	s_cbranch_scc0 .LBB0_590
	s_ashr_i32 s52, s84, 5
	s_ashr_i32 s53, s52, 31
	s_lshl_b64 s[4:5], s[52:53], 12
	v_mov_b32_e32 v5, s5
	v_or_b32_e32 v4, s4, v154
	v_mov_b32_e32 v9, s5
	v_or_b32_e32 v8, s4, v156
	v_readlane_b32 s4, v255, 15
	v_lshlrev_b64 v[4:5], 11, v[4:5]
	v_readlane_b32 s5, v255, 16
	v_lshl_add_u64 v[6:7], s[86:87], 0, v[4:5]
	s_mov_b32 s7, s91
	v_lshl_add_u64 v[4:5], s[4:5], 0, v[4:5]
	v_lshlrev_b64 v[8:9], 12, v[8:9]
	v_lshl_add_u64 v[4:5], v[4:5], 0, s[6:7]
	v_mov_b32_e32 v169, v2
	s_and_b32 s11, s84, 7
	v_lshl_add_u64 v[16:17], v[4:5], 0, v[168:169]
	v_lshl_add_u64 v[4:5], s[88:89], 0, v[8:9]
	s_mov_b32 s55, s91
	v_lshl_add_u64 v[4:5], v[4:5], 0, s[54:55]
	s_lshl_b32 s4, s11, 7
	s_mov_b32 s5, s91
	v_lshl_add_u64 v[56:57], v[4:5], 0, s[4:5]
	s_mov_b32 s4, 0x10000
	v_lshl_add_u64 v[6:7], v[6:7], 0, s[6:7]
	v_add_co_u32_e32 v8, vcc, s4, v16
	v_lshl_add_u64 v[54:55], v[6:7], 0, v[168:169]
	s_nop 0
	v_addc_co_u32_e32 v9, vcc, 0, v17, vcc
	v_add_co_u32_e32 v58, vcc, s4, v54
	s_mov_b32 s4, 0x20000
	s_nop 0
	v_addc_co_u32_e32 v59, vcc, 0, v55, vcc
	v_add_co_u32_e32 v12, vcc, s4, v16
	global_load_dwordx4 v[114:117], v[16:17], off
	global_load_dwordx4 v[4:7], v[54:55], off
	v_addc_co_u32_e32 v13, vcc, 0, v17, vcc
	v_add_co_u32_e32 v60, vcc, s4, v54
	s_mov_b32 s4, 0x30000
	s_nop 0
	v_addc_co_u32_e32 v61, vcc, 0, v55, vcc
	v_add_co_u32_e32 v16, vcc, s4, v16
	v_mov_b32_e32 v171, v2
	s_nop 0
	v_addc_co_u32_e32 v17, vcc, 0, v17, vcc
	v_add_co_u32_e32 v62, vcc, s4, v54
	global_load_dwordx4 v[118:121], v[8:9], off
	s_nop 0
	global_load_dwordx4 v[8:11], v[58:59], off
	global_load_dwordx4 v[134:137], v[12:13], off
	s_nop 0
	global_load_dwordx4 v[12:15], v[60:61], off
	v_addc_co_u32_e32 v63, vcc, 0, v55, vcc
	global_load_dwordx4 v[142:145], v[16:17], off
	global_load_dwordx4 v[50:53], v[62:63], off
	v_lshl_add_u64 v[16:17], v[56:57], 0, v[170:171]
	s_mov_b32 s4, 0x40000
	v_add_co_u32_e32 v56, vcc, s4, v16
	s_lshl_b32 s4, s90, 6
	s_nop 0
	v_addc_co_u32_e32 v57, vcc, 0, v17, vcc
	global_load_dwordx4 v[122:125], v[16:17], off
	global_load_dwordx4 v[126:129], v[56:57], off
	s_add_i32 s4, s4, 0
	s_add_i32 s4, s4, 0x15800
	v_or_b32_e32 v16, s38, v1
	v_mov_b32_e32 v17, s4
	s_movk_i32 s4, 0x210
	v_mad_u32_u24 v16, v16, s4, v17
	v_add_u32_e32 v169, v16, v157
	v_cvt_pk_bf16_f32 v16, v18, v19
	v_cvt_pk_bf16_f32 v17, v20, v21
	v_cvt_pk_bf16_f32 v56, v22, v23
	v_cvt_pk_bf16_f32 v57, v24, v25
	ds_write2_b64 v169, v[16:17], v[56:57] offset1:2
	v_cvt_pk_bf16_f32 v16, v26, v27
	v_cvt_pk_bf16_f32 v17, v28, v29
	v_cvt_pk_bf16_f32 v56, v30, v31
	v_cvt_pk_bf16_f32 v57, v32, v33
	ds_write2_b64 v169, v[16:17], v[56:57] offset0:4 offset1:6
	v_cvt_pk_bf16_f32 v16, v34, v35
	v_cvt_pk_bf16_f32 v17, v36, v37
	v_cvt_pk_bf16_f32 v56, v38, v39
	v_cvt_pk_bf16_f32 v57, v40, v41
	ds_write2_b64 v169, v[16:17], v[56:57] offset0:32 offset1:34
	v_mul_f32_e32 v56, v224, v159
	v_cmp_gt_f32_e32 vcc, s0, v56
	v_cvt_pk_bf16_f32 v16, v42, v43
	v_cvt_pk_bf16_f32 v17, v44, v45
	v_cndmask_b32_e32 v56, 0, v220, vcc
	v_fmac_f32_e32 v56, v224, v159
	v_exp_f32_e32 v65, v56
	v_cvt_pk_bf16_f32 v56, v46, v47
	v_cvt_pk_bf16_f32 v57, v48, v49
	ds_write2_b64 v169, v[16:17], v[56:57] offset0:36 offset1:38
	v_mul_f32_e32 v16, v224, v194
	v_mul_f32_e32 v3, 0x43000000, v224
	v_cndmask_b32_e32 v64, 0, v222, vcc
	v_cmp_gt_f32_e32 vcc, s0, v16
	s_lshl_b32 s62, s9, 9
	s_waitcnt vmcnt(0)
	ds_write_b128 v223, v[4:7] offset:34816
	ds_write_b128 v223, v[8:11] offset:43520
	ds_write_b128 v223, v[12:15] offset:52224
	ds_write_b128 v223, v[50:53] offset:60928
	v_cndmask_b32_e32 v16, 0, v222, vcc
	v_cndmask_b32_e32 v17, 0, v220, vcc
	v_cmp_gt_f32_e32 vcc, s0, v3
	s_lshl_b32 s55, s10, 7
	s_lshl_b32 s58, s9, 6
	v_cndmask_b32_e32 v3, 0, v220, vcc
	v_fmac_f32_e32 v3, 0x43000000, v224
	v_exp_f32_e32 v3, v3
	s_lshl_b32 s59, s10, 3
	s_lshl_b32 s66, s90, 5
	s_and_b64 s[4:5], vcc, exec
	s_cselect_b32 s4, 0xffffffc0, 0
	v_ldexp_f32 v176, v3, s4
	s_lshl_b32 s4, s8, 2
	s_lshr_b32 s5, 0x31002210, s4
	s_lshr_b32 s4, 0x33323210, s4
	s_cmpk_lt_u32 s57, 0x80
	s_cselect_b64 s[80:81], -1, 0
	s_cmpk_gt_u32 s57, 0x7f
	s_cselect_b64 s[72:73], -1, 0
	s_lshl_b32 s4, s4, 5
	s_lshl_b32 s5, s5, 5
	s_and_b32 s39, s4, 0x60
	s_lshl_b32 s4, s8, 4
	s_lshl_b32 s6, s8, 5
	s_and_b32 s5, s5, 0x60
	s_and_b32 s4, s4, 0x3fffffe0
	s_and_b32 s6, s6, 32
	s_cmpk_gt_u32 s57, 0xff
	s_cselect_b64 s[78:79], -1, 0
	s_cmpk_gt_u32 s57, 0x17f
	s_cselect_b64 s[76:77], -1, 0
	s_lshl_b64 s[60:61], s[52:53], 23
	v_fmac_f32_e32 v17, v224, v194
	s_or_b32 s60, s60, s62
	s_lshl_b64 s[68:69], s[52:53], 24
	v_exp_f32_e32 v17, v17
	s_add_u32 s62, s55, s54
	v_and_b32_e32 v8, 4, v156
	s_addc_u32 s63, 0, 0
	s_lshl_b32 s57, s56, 2
	v_or_b32_e32 v8, s5, v8
	s_or_b32 s57, s57, s59
	v_or_b32_e32 v4, s39, v1
	v_or_b32_e32 v7, s4, v201
	v_or_b32_e32 v9, 2, v8
	v_or_b32_e32 v10, 3, v8
	v_or_b32_e32 v11, 8, v8
	v_add_u32_e32 v57, s39, v199
	s_lshl_b64 s[64:65], s[90:91], 13
	s_or_b32 s57, s57, s58
	v_ldexp_f32 v174, v17, v16
	v_or_b32_e32 v3, s5, v1
	v_or_b32_e32 v5, s4, v1
	v_or_b32_e32 v6, s6, v1
	v_lshl_add_u32 v225, v7, 1, v196
	v_or_b32_e32 v7, s6, v201
	v_lshlrev_b32_e32 v227, 1, v8
	v_cmp_gt_u32_e64 s[4:5], v8, v4
	v_cmp_lt_u32_e64 s[6:7], v8, v4
	v_cmp_gt_u32_e64 s[8:9], v9, v4
	v_cmp_gt_u32_e64 s[10:11], v10, v4
	v_cmp_gt_u32_e64 s[12:13], v11, v4
	v_or_b32_e32 v12, 9, v8
	v_or_b32_e32 v13, 10, v8
	v_or_b32_e32 v14, 11, v8
	v_or_b32_e32 v15, 16, v8
	v_or_b32_e32 v16, 17, v8
	v_or_b32_e32 v17, 18, v8
	v_or_b32_e32 v50, 19, v8
	v_or_b32_e32 v51, 24, v8
	v_or_b32_e32 v52, 25, v8
	v_or_b32_e32 v53, 26, v8
	v_or_b32_e32 v54, 27, v8
	v_or_b32_e32 v56, s38, v201
	v_cmp_gt_u32_e64 s[38:39], v8, v57
	v_cmp_lt_u32_e64 s[40:41], v8, v57
	v_cmp_gt_u32_e64 s[42:43], v9, v57
	v_cmp_gt_u32_e64 s[44:45], v10, v57
	v_cmp_gt_u32_e64 s[46:47], v11, v57
	s_or_b64 s[62:63], s[62:63], s[68:69]
	s_lshl_b64 s[52:53], s[52:53], 20
	s_or_b32 s57, s64, s57
	v_or_b32_e32 v8, s66, v155
	v_or_b32_e32 v9, s66, v252
	v_or_b32_e32 v10, s66, v253
	v_or_b32_e32 v11, s66, v254
	s_add_u32 s64, s57, s52
	v_cvt_f32_u32_e32 v8, v8
	v_cvt_f32_u32_e32 v9, v9
	v_cvt_f32_u32_e32 v10, v10
	v_cvt_f32_u32_e32 v11, v11
	s_addc_u32 s65, s65, s53
	s_lshl_b32 s56, s56, 6
	s_lshl_b64 s[58:59], s[90:91], 17
	s_or_b32 s55, s56, s55
	v_cmp_gt_u32_e64 s[14:15], v12, v4
	v_cmp_gt_u32_e64 s[16:17], v13, v4
	v_cmp_gt_u32_e64 s[18:19], v14, v4
	v_cmp_gt_u32_e64 s[20:21], v15, v4
	v_cmp_gt_u32_e64 s[48:49], v12, v57
	v_cmp_gt_u32_e64 s[50:51], v13, v57
	v_cmp_gt_u32_e64 s[52:53], v14, v57
	s_add_u32 s56, s55, s54
	v_cmp_gt_u32_e64 s[54:55], v15, v57
	v_or_b32_e32 v12, s66, v198
	v_or_b32_e32 v13, s66, v206
	v_or_b32_e32 v14, s66, v207
	v_or_b32_e32 v15, s66, v208
	s_addc_u32 s57, 0, 0
	v_add_f32_e32 v228, 0xc2fe0000, v8
	v_add_f32_e32 v229, 0xc2fe0000, v9
	v_add_f32_e32 v230, 0xc2fe0000, v10
	v_add_f32_e32 v231, 0xc2fe0000, v11
	v_cvt_f32_u32_e32 v8, v12
	v_cvt_f32_u32_e32 v9, v13
	v_cvt_f32_u32_e32 v10, v14
	v_cvt_f32_u32_e32 v11, v15
	s_or_b64 s[56:57], s[56:57], s[58:59]
	s_add_u32 s68, s56, s68
	v_cmp_gt_u32_e64 s[22:23], v16, v4
	v_cmp_gt_u32_e64 s[24:25], v17, v4
	v_cmp_gt_u32_e64 s[26:27], v50, v4
	s_addc_u32 s69, s57, s69
	v_cmp_gt_u32_e64 s[56:57], v16, v57
	v_cmp_gt_u32_e64 s[58:59], v17, v57
	v_lshl_add_u64 v[178:179], s[60:61], 0, v[162:163]
	v_cmp_gt_u32_e64 s[60:61], v50, v57
	v_or_b32_e32 v16, s66, v209
	v_or_b32_e32 v17, s66, v210
	v_or_b32_e32 v50, s66, v211
	v_or_b32_e32 v59, s66, v212
	v_add_f32_e32 v232, 0xc2fe0000, v8
	v_add_f32_e32 v233, 0xc2fe0000, v9
	v_add_f32_e32 v234, 0xc2fe0000, v10
	v_add_f32_e32 v235, 0xc2fe0000, v11
	v_cvt_f32_u32_e32 v8, v16
	v_cvt_f32_u32_e32 v9, v17
	v_cvt_f32_u32_e32 v10, v50
	v_cvt_f32_u32_e32 v11, v59
	v_or_b32_e32 v60, s66, v213
	v_or_b32_e32 v61, s66, v214
	v_or_b32_e32 v62, s66, v215
	v_or_b32_e32 v63, s66, v216
	v_add_f32_e32 v236, 0xc2fe0000, v8
	v_add_f32_e32 v237, 0xc2fe0000, v9
	v_add_f32_e32 v238, 0xc2fe0000, v10
	v_add_f32_e32 v239, 0xc2fe0000, v11
	v_cvt_f32_u32_e32 v8, v60
	v_cvt_f32_u32_e32 v9, v61
	v_cvt_f32_u32_e32 v10, v62
	v_cvt_f32_u32_e32 v11, v63
	v_or_b32_e32 v55, s66, v1
	v_ldexp_f32 v172, v65, v64
	v_mul_u32_u24_e32 v3, 0x110, v3
	v_mad_u32_u24 v171, v4, s93, 0
	v_mul_lo_u32 v5, v5, s93
	v_mul_u32_u24_e32 v6, 0x210, v6
	v_lshlrev_b32_e32 v7, 1, v7
	v_cmp_gt_u32_e64 s[28:29], v51, v4
	v_cmp_gt_u32_e64 s[30:31], v52, v4
	v_cmp_gt_u32_e64 s[34:35], v53, v4
	v_cmp_gt_u32_e64 s[36:37], v54, v4
	v_add_u32_e32 v4, 0, v227
	v_mul_lo_u32 v55, v55, s93
	v_lshlrev_b32_e32 v56, 1, v56
	v_mul_u32_u24_e32 v58, 0x110, v57
	s_mov_b32 s85, 32
	v_add_u32_e32 v226, 0x8800, v225
	v_lshl_add_u64 v[180:181], s[62:63], 0, v[164:165]
	v_cmp_gt_u32_e64 s[62:63], v51, v57
	v_lshl_add_u64 v[182:183], s[64:65], 0, v[160:161]
	v_cmp_gt_u32_e64 s[64:65], v52, v57
	v_lshl_add_u64 v[184:185], s[68:69], 0, v[166:167]
	v_cmp_gt_u32_e64 s[66:67], v53, v57
	v_mov_b32_e32 v173, v172
	v_mov_b32_e32 v186, v172
	v_mov_b32_e32 v187, v172
	v_mov_b32_e32 v175, v174
	v_mov_b32_e32 v188, v174
	v_mov_b32_e32 v189, v174
	v_add_f32_e32 v240, 0xc2fe0000, v8
	v_add_f32_e32 v241, 0xc2fe0000, v9
	v_add_f32_e32 v242, 0xc2fe0000, v10
	v_add_f32_e32 v243, 0xc2fe0000, v11
	v_mov_b32_e32 v190, v176
	v_mov_b32_e32 v191, v176
	v_add_u32_e32 v244, v4, v58
	v_add_u32_e32 v245, v195, v3
	v_add_u32_e32 v246, v195, v5
	v_add_u32_e32 v247, v217, v6
	v_add_u32_e32 v248, v197, v7
	v_add_u32_e32 v249, v195, v55
	v_add_u32_e32 v250, v200, v56
	v_cmp_gt_u32_e64 s[68:69], v54, v57
	v_lshl_add_u64 v[192:193], s[82:83], 0, v[178:179]
	v_add_co_u32_e32 v4, vcc, 0x7a00000, v192
	s_nop 1
	v_addc_co_u32_e32 v5, vcc, 0, v193, vcc
	v_add_co_u32_e32 v6, vcc, 0x7a10000, v192
	s_nop 1
	v_addc_co_u32_e32 v7, vcc, 0, v193, vcc
	global_load_dwordx4 v[154:157], v[4:5], off offset:256
	global_load_dwordx4 v[160:163], v[6:7], off offset:256
	v_add_co_u32_e32 v4, vcc, 0x7a20000, v192
	s_nop 1
	v_addc_co_u32_e32 v5, vcc, 0, v193, vcc
	v_add_co_u32_e32 v6, vcc, 0x7a30000, v192
	s_nop 1
	v_addc_co_u32_e32 v7, vcc, 0, v193, vcc
	global_load_dwordx4 v[164:167], v[4:5], off offset:256
	global_load_dwordx4 v[194:197], v[6:7], off offset:256
	v_add_co_u32_e32 v4, vcc, 0xba00000, v192
	s_nop 1
	v_addc_co_u32_e32 v5, vcc, 0, v193, vcc
	v_add_co_u32_e32 v6, vcc, 0xba10000, v192
	s_nop 1
	v_addc_co_u32_e32 v7, vcc, 0, v193, vcc
	global_load_dwordx4 v[198:201], v[4:5], off offset:256
	global_load_dwordx4 v[206:209], v[6:7], off offset:256
	v_add_co_u32_e32 v4, vcc, 0xba20000, v192
	s_nop 1
	v_addc_co_u32_e32 v5, vcc, 0, v193, vcc
	v_add_co_u32_e32 v6, vcc, 0xba30000, v192
	s_nop 1
	v_addc_co_u32_e32 v7, vcc, 0, v193, vcc
	global_load_dwordx4 v[210:213], v[4:5], off offset:256
	global_load_dwordx4 v[214:217], v[6:7], off offset:256
	v_add_co_u32_e32 v4, vcc, 0xba40000, v192
	s_nop 1
	v_addc_co_u32_e32 v5, vcc, 0, v193, vcc
	v_add_co_u32_e32 v6, vcc, 0xba50000, v192
	s_nop 1
	v_addc_co_u32_e32 v7, vcc, 0, v193, vcc
	global_load_dwordx4 v[130:133], v[4:5], off
	global_load_dwordx4 v[138:141], v[6:7], off
	v_add_co_u32_e32 v4, vcc, 0xba60000, v192
	s_nop 1
	v_addc_co_u32_e32 v5, vcc, 0, v193, vcc
	v_add_co_u32_e32 v6, vcc, 0xba70000, v192
	s_nop 1
	v_addc_co_u32_e32 v7, vcc, 0, v193, vcc
	global_load_dwordx4 v[146:149], v[4:5], off
	global_load_dwordx4 v[150:153], v[6:7], off
	s_waitcnt vmcnt(0)
	s_branch .LBB0_593

.LBB0_593:
	v_lshl_add_u64 v[192:193], s[82:83], 0, v[178:179]
	s_waitcnt vmcnt(44)
	ds_write_b128 v223, v[114:117]
	ds_write_b128 v223, v[118:121] offset:8704
	ds_write_b128 v223, v[134:137] offset:17408
	ds_write_b128 v223, v[142:145] offset:26112
	v_add_co_u32_e32 v4, vcc, 0x7a40000, v192
	s_nop 1
	v_addc_co_u32_e32 v5, vcc, 0, v193, vcc
	v_add_co_u32_e32 v6, vcc, 0x7a50000, v192
	s_nop 1
	v_addc_co_u32_e32 v7, vcc, 0, v193, vcc
	global_load_dwordx4 v[114:117], v[4:5], off
	global_load_dwordx4 v[118:121], v[6:7], off
	v_add_co_u32_e32 v4, vcc, 0x7a60000, v192
	s_nop 1
	v_addc_co_u32_e32 v5, vcc, 0, v193, vcc
	v_add_co_u32_e32 v6, vcc, 0x7a70000, v192
	s_nop 1
	v_addc_co_u32_e32 v7, vcc, 0, v193, vcc
	global_load_dwordx4 v[134:137], v[4:5], off
	global_load_dwordx4 v[142:145], v[6:7], off
	v_lshlrev_b32_e32 v8, 16, v124
	v_and_b32_e32 v9, 0xffff0000, v124
	v_lshlrev_b32_e32 v4, 16, v122
	v_and_b32_e32 v5, 0xffff0000, v122
	v_lshlrev_b32_e32 v6, 16, v123
	v_and_b32_e32 v7, 0xffff0000, v123
	v_lshlrev_b32_e32 v10, 16, v125
	v_and_b32_e32 v11, 0xffff0000, v125
	v_pk_mul_f32 v[6:7], v[186:187], v[6:7]
	v_pk_mul_f32 v[4:5], v[172:173], v[4:5]
	v_pk_mul_f32 v[10:11], v[186:187], v[10:11]
	v_pk_mul_f32 v[8:9], v[172:173], v[8:9]
	v_cvt_pk_bf16_f32 v4, v4, v5
	v_cvt_pk_bf16_f32 v5, v6, v7
	v_cvt_pk_bf16_f32 v6, v8, v9
	v_cvt_pk_bf16_f32 v7, v10, v11
	ds_write_b128 v219, v[4:7]
	v_lshlrev_b32_e32 v4, 16, v126
	v_and_b32_e32 v5, 0xffff0000, v126
	v_lshlrev_b32_e32 v6, 16, v127
	v_and_b32_e32 v7, 0xffff0000, v127
	v_lshlrev_b32_e32 v8, 16, v128
	v_and_b32_e32 v9, 0xffff0000, v128
	v_lshlrev_b32_e32 v10, 16, v129
	v_and_b32_e32 v11, 0xffff0000, v129
	v_pk_mul_f32 v[6:7], v[188:189], v[6:7]
	v_pk_mul_f32 v[4:5], v[174:175], v[4:5]
	v_pk_mul_f32 v[10:11], v[188:189], v[10:11]
	v_pk_mul_f32 v[8:9], v[174:175], v[8:9]
	v_cvt_pk_bf16_f32 v4, v4, v5
	v_cvt_pk_bf16_f32 v5, v6, v7
	v_cvt_pk_bf16_f32 v6, v8, v9
	v_cvt_pk_bf16_f32 v7, v10, v11
	ds_write_b128 v219, v[4:7] offset:9216
	v_lshl_add_u64 v[4:5], s[82:83], 0, v[180:181]
	v_add_co_u32_e32 v6, vcc, 0xfa80000, v4
	s_nop 1
	v_addc_co_u32_e32 v7, vcc, 0, v5, vcc
	v_add_co_u32_e32 v4, vcc, 0xfac0000, v4
	s_nop 1
	v_addc_co_u32_e32 v5, vcc, 0, v5, vcc
	global_load_dwordx4 v[122:125], v[6:7], off
	global_load_dwordx4 v[126:129], v[4:5], off
	s_waitcnt lgkmcnt(0)
	s_barrier
	v_add_u32_e32 v251, v171, v158
	ds_read_b128 v[4:7], v245 offset:34816
	ds_read_b128 v[8:11], v251
	v_cndmask_b32_e64 v3, 0, 1, s[72:73]
	v_cmp_ne_u32_e64 s[70:71], 1, v3
	s_andn2_b64 vcc, exec, s[72:73]
	s_mov_b64 s[74:75], -1
	s_cbranch_vccnz .LBB0_595
	s_waitcnt lgkmcnt(0)
	v_mfma_f32_32x32x16_bf16 v[82:97], v[4:7], v[8:11], 0
	ds_read_b128 v[12:15], v245 offset:34848
	ds_read_b128 v[50:53], v251 offset:32
	s_mov_b64 s[74:75], 0
	s_waitcnt lgkmcnt(0)
	v_mfma_f32_32x32x16_bf16 v[82:97], v[12:15], v[50:53], v[82:97]
	ds_read_b128 v[12:15], v245 offset:34880
	ds_read_b128 v[50:53], v251 offset:64
	s_waitcnt lgkmcnt(0)
	v_mfma_f32_32x32x16_bf16 v[82:97], v[12:15], v[50:53], v[82:97]
	ds_read_b128 v[12:15], v245 offset:34912
	ds_read_b128 v[50:53], v251 offset:96
	s_waitcnt lgkmcnt(0)
	v_mfma_f32_32x32x16_bf16 v[82:97], v[12:15], v[50:53], v[82:97]
	ds_read_b128 v[12:15], v245 offset:34944
	ds_read_b128 v[50:53], v251 offset:128
	s_waitcnt lgkmcnt(0)
	v_mfma_f32_32x32x16_bf16 v[82:97], v[12:15], v[50:53], v[82:97]
	ds_read_b128 v[12:15], v245 offset:34976
	ds_read_b128 v[50:53], v251 offset:160
	s_waitcnt lgkmcnt(0)
	v_mfma_f32_32x32x16_bf16 v[82:97], v[12:15], v[50:53], v[82:97]
	ds_read_b128 v[12:15], v245 offset:35008
	ds_read_b128 v[50:53], v251 offset:192
	s_waitcnt lgkmcnt(0)
	v_mfma_f32_32x32x16_bf16 v[82:97], v[12:15], v[50:53], v[82:97]
	ds_read_b128 v[12:15], v245 offset:35040
	ds_read_b128 v[50:53], v251 offset:224
	s_waitcnt lgkmcnt(0)
	v_mfma_f32_32x32x16_bf16 v[82:97], v[12:15], v[50:53], v[82:97]

.LBB0_598:
	ds_read_b128 v[4:7], v246
	ds_read_b128 v[8:11], v247
	ds_read_b128 v[12:15], v246 offset:32
	ds_read_b128 v[98:101], v247 offset:32
	v_mov_b32_e32 v177, v176
	v_pk_mul_f32 v[18:19], v[190:191], v[18:19]
	s_waitcnt lgkmcnt(2)
	v_mfma_f32_32x32x16_bf16 v[50:65], v[4:7], v[8:11], 0
	v_mul_f32_e64 v32, v176, v32
	v_mul_f32_e64 v33, v177, v33
	v_mul_f32_e64 v30, v176, v30
	v_mul_f32_e64 v31, v177, v31
	v_mul_f32_e64 v28, v176, v28
	v_mul_f32_e64 v29, v177, v29
	v_pk_mul_f32 v[26:27], v[176:177], v[26:27]
	v_pk_mul_f32 v[24:25], v[176:177], v[24:25]
	v_pk_mul_f32 v[22:23], v[176:177], v[22:23]
	v_pk_mul_f32 v[20:21], v[176:177], v[20:21]
	s_waitcnt lgkmcnt(0)
	v_mfma_f32_32x32x16_bf16 v[50:65], v[12:15], v[98:101], v[50:65]
	ds_read_b128 v[4:7], v246 offset:64
	ds_read_b128 v[8:11], v247 offset:64
	ds_read_b128 v[12:15], v246 offset:96
	ds_read_b128 v[98:101], v247 offset:96
	s_cmp_lg_u32 s85, 1
	s_cselect_b64 s[74:75], -1, 0
	s_cmp_eq_u32 s85, 1
	s_waitcnt lgkmcnt(2)
	v_mfma_f32_32x32x16_bf16 v[50:65], v[4:7], v[8:11], v[50:65]
	s_waitcnt lgkmcnt(0)
	v_mfma_f32_32x32x16_bf16 v[50:65], v[12:15], v[98:101], v[50:65]
	ds_read_b128 v[4:7], v246 offset:128
	ds_read_b128 v[8:11], v247 offset:128
	ds_read_b128 v[12:15], v246 offset:160
	ds_read_b128 v[98:101], v247 offset:160
	s_waitcnt lgkmcnt(2)
	v_mfma_f32_32x32x16_bf16 v[50:65], v[4:7], v[8:11], v[50:65]
	ds_read_b64_tr_b16 v[4:5], v225 offset:34816
	ds_read_b64_tr_b16 v[6:7], v225 offset:35088
	ds_read_b64_tr_b16 v[8:9], v225 offset:39168
	ds_read_b64_tr_b16 v[10:11], v225 offset:39440
	ds_read_b64_tr_b16 v[102:103], v248
	ds_read_b64_tr_b16 v[104:105], v248 offset:144
	ds_read_b64_tr_b16 v[106:107], v248 offset:2304
	ds_read_b64_tr_b16 v[108:109], v248 offset:2448
	s_waitcnt lgkmcnt(2)
	v_mfma_f32_32x32x16_bf16 v[18:33], v[4:7], v[102:105], v[18:33]
	s_waitcnt lgkmcnt(0)
	v_mfma_f32_32x32x16_bf16 v[18:33], v[8:11], v[106:109], v[18:33]
	v_mfma_f32_32x32x16_bf16 v[50:65], v[12:15], v[98:101], v[50:65]
	ds_read_b64_tr_b16 v[4:5], v225 offset:43520
	ds_read_b64_tr_b16 v[6:7], v225 offset:43792
	ds_read_b64_tr_b16 v[8:9], v248 offset:4608
	ds_read_b64_tr_b16 v[10:11], v248 offset:4752
	ds_read_b64_tr_b16 v[12:13], v225 offset:47872
	ds_read_b64_tr_b16 v[14:15], v225 offset:48144
	ds_read_b64_tr_b16 v[98:99], v248 offset:6912
	ds_read_b64_tr_b16 v[100:101], v248 offset:7056
	s_waitcnt lgkmcnt(4)
	v_mfma_f32_32x32x16_bf16 v[18:33], v[4:7], v[8:11], v[18:33]
	s_waitcnt lgkmcnt(0)
	v_mfma_f32_32x32x16_bf16 v[18:33], v[12:15], v[98:101], v[18:33]
	ds_read_b64_tr_b16 v[4:5], v225 offset:52224
	ds_read_b64_tr_b16 v[6:7], v225 offset:52496
	ds_read_b64_tr_b16 v[8:9], v248 offset:9216
	ds_read_b64_tr_b16 v[10:11], v248 offset:9360
	ds_read_b64_tr_b16 v[12:13], v225 offset:56576
	ds_read_b64_tr_b16 v[14:15], v225 offset:56848
	ds_read_b64_tr_b16 v[98:99], v248 offset:11520
	ds_read_b64_tr_b16 v[100:101], v248 offset:11664
	s_waitcnt lgkmcnt(4)
	v_mfma_f32_32x32x16_bf16 v[18:33], v[4:7], v[8:11], v[18:33]
	ds_read_b128 v[4:7], v246 offset:192
	ds_read_b128 v[8:11], v246 offset:224
	ds_read_b128 v[102:105], v247 offset:192
	ds_read_b128 v[106:109], v247 offset:224
	s_waitcnt lgkmcnt(4)
	v_mfma_f32_32x32x16_bf16 v[18:33], v[12:15], v[98:101], v[18:33]
	ds_read_b64_tr_b16 v[12:13], v225 offset:60928
	ds_read_b64_tr_b16 v[14:15], v225 offset:61200
	ds_read_b64_tr_b16 v[98:99], v225 offset:65280
	ds_read_b64_tr_b16 v[100:101], v226 offset:30736
	ds_read_b64_tr_b16 v[110:111], v248 offset:13824
	ds_read_b64_tr_b16 v[112:113], v248 offset:13968
	ds_read_b64_tr_b16 v[202:203], v248 offset:16128
	ds_read_b64_tr_b16 v[204:205], v248 offset:16272
	s_waitcnt lgkmcnt(0)
	s_barrier
	s_waitcnt vmcnt(42)
	ds_write_b128 v223, v[154:157]
	ds_write_b128 v223, v[198:201] offset:34816
	ds_write_b128 v223, v[160:163] offset:8704
	ds_write_b128 v223, v[206:209] offset:43520
	ds_write_b128 v223, v[164:167] offset:17408
	ds_write_b128 v223, v[210:213] offset:52224
	ds_write_b128 v223, v[194:197] offset:26112
	ds_write_b128 v223, v[214:217] offset:60928
	v_mfma_f32_32x32x16_bf16 v[18:33], v[12:15], v[110:113], v[18:33]
	v_mfma_f32_32x32x16_bf16 v[50:65], v[4:7], v[102:105], v[50:65]
	v_mfma_f32_32x32x16_bf16 v[18:33], v[98:101], v[202:205], v[18:33]
	v_mfma_f32_32x32x16_bf16 v[50:65], v[8:11], v[106:109], v[50:65]
	s_nop 10
	v_cvt_pk_bf16_f32 v12, v18, v19
	v_cvt_pk_bf16_f32 v13, v20, v21
	v_cvt_pk_bf16_f32 v14, v22, v23
	v_cvt_pk_bf16_f32 v15, v24, v25
	v_cvt_pk_bf16_f32 v4, v26, v27
	v_cvt_pk_bf16_f32 v5, v28, v29
	v_cvt_pk_bf16_f32 v6, v30, v31
	v_cvt_pk_bf16_f32 v7, v32, v33
	ds_write2_b64 v169, v[12:13], v[14:15] offset1:2
	ds_write2_b64 v169, v[4:5], v[6:7] offset0:4 offset1:6
	v_add_co_u32_e32 v4, vcc, 0x7a40000, v192
	s_nop 1
	v_addc_co_u32_e32 v5, vcc, 0, v193, vcc
	v_add_co_u32_e32 v6, vcc, 0x7a50000, v192
	s_nop 1
	v_addc_co_u32_e32 v7, vcc, 0, v193, vcc
	global_load_dwordx4 v[154:157], v[4:5], off offset:256
	global_load_dwordx4 v[160:163], v[6:7], off offset:256
	v_add_co_u32_e32 v4, vcc, 0x7a60000, v192
	s_nop 1
	v_addc_co_u32_e32 v5, vcc, 0, v193, vcc
	v_add_co_u32_e32 v6, vcc, 0x7a70000, v192
	s_nop 1
	v_addc_co_u32_e32 v7, vcc, 0, v193, vcc
	global_load_dwordx4 v[164:167], v[4:5], off offset:256
	global_load_dwordx4 v[194:197], v[6:7], off offset:256
	v_add_co_u32_e32 v4, vcc, 0xba40000, v192
	s_nop 1
	v_addc_co_u32_e32 v5, vcc, 0, v193, vcc
	v_add_co_u32_e32 v6, vcc, 0xba50000, v192
	s_nop 1
	v_addc_co_u32_e32 v7, vcc, 0, v193, vcc
	global_load_dwordx4 v[198:201], v[4:5], off offset:256
	global_load_dwordx4 v[206:209], v[6:7], off offset:256
	v_add_co_u32_e32 v4, vcc, 0xba60000, v192
	s_nop 1
	v_addc_co_u32_e32 v5, vcc, 0, v193, vcc
	v_add_co_u32_e32 v6, vcc, 0xba70000, v192
	s_nop 1
	v_addc_co_u32_e32 v7, vcc, 0, v193, vcc
	global_load_dwordx4 v[210:213], v[4:5], off offset:256
	global_load_dwordx4 v[214:217], v[6:7], off offset:256

.LBB0_610:
	v_mov_b32_e32 v3, v224
	s_waitcnt vmcnt(14)
	ds_write_b128 v223, v[130:133] offset:34816
	ds_write_b128 v223, v[138:141] offset:43520
	ds_write_b128 v223, v[146:149] offset:52224
	ds_write_b128 v223, v[150:153] offset:60928
	v_add_co_u32_e32 v4, vcc, 0xba80000, v192
	s_nop 1
	v_addc_co_u32_e32 v5, vcc, 0, v193, vcc
	v_add_co_u32_e32 v6, vcc, 0xba90000, v192
	s_nop 1
	v_addc_co_u32_e32 v7, vcc, 0, v193, vcc
	global_load_dwordx4 v[130:133], v[4:5], off
	global_load_dwordx4 v[138:141], v[6:7], off
	v_add_co_u32_e32 v4, vcc, 0xbaa0000, v192
	s_nop 1
	v_addc_co_u32_e32 v5, vcc, 0, v193, vcc
	v_add_co_u32_e32 v6, vcc, 0xbab0000, v192
	s_nop 1
	v_addc_co_u32_e32 v7, vcc, 0, v193, vcc
	global_load_dwordx4 v[146:149], v[4:5], off
	global_load_dwordx4 v[150:153], v[6:7], off
